# attention: straight-line software-pipelined PV (32 MFMA, 6 LDS fragment buffers) when both query blocks are active
# baseline (speedup 1.0000x reference)
.Lpv_fast:
	ds_read_b64 v[164:165], v202 offset:18432
	ds_read_b64 v[166:167], v203 offset:18432
	ds_read_b64 v[168:169], v204 offset:18432
	ds_read_b64 v[170:171], v205 offset:18432
	ds_read_b64 v[172:173], v206 offset:18432
	ds_read_b64 v[174:175], v207 offset:18432
	ds_read_b64 v[120:121], v208 offset:18432
	ds_read_b64 v[122:123], v209 offset:18432
	ds_read_b64 v[124:125], v210 offset:18432
	ds_read_b64 v[126:127], v211 offset:18432
	ds_read_b64 v[128:129], v212 offset:18432
	ds_read_b64 v[130:131], v213 offset:18432
	s_waitcnt lgkmcnt(10)
	v_mfma_f32_16x16x32_bf16 v[92:95], v[164:167], v[152:155], v[92:95]
	v_mfma_f32_16x16x32_bf16 v[72:75], v[164:167], v[144:147], v[72:75]
	ds_read_b64 v[164:165], v214 offset:18432
	ds_read_b64 v[166:167], v215 offset:18432
	s_waitcnt lgkmcnt(10)
	v_mfma_f32_16x16x32_bf16 v[96:99], v[168:171], v[152:155], v[96:99]
	v_mfma_f32_16x16x32_bf16 v[76:79], v[168:171], v[144:147], v[76:79]
	ds_read_b64 v[168:169], v216 offset:18432
	ds_read_b64 v[170:171], v217 offset:18432
	s_waitcnt lgkmcnt(10)
	v_mfma_f32_16x16x32_bf16 v[104:107], v[172:175], v[152:155], v[104:107]
	v_mfma_f32_16x16x32_bf16 v[80:83], v[172:175], v[144:147], v[80:83]
	ds_read_b64 v[172:173], v218 offset:18432
	ds_read_b64 v[174:175], v220 offset:18432
	s_waitcnt lgkmcnt(10)
	v_mfma_f32_16x16x32_bf16 v[108:111], v[120:123], v[152:155], v[108:111]
	v_mfma_f32_16x16x32_bf16 v[64:67], v[120:123], v[144:147], v[64:67]
	ds_read_b64 v[120:121], v221 offset:18432
	ds_read_b64 v[122:123], v222 offset:18432
	s_waitcnt lgkmcnt(10)
	v_mfma_f32_16x16x32_bf16 v[92:95], v[124:127], v[156:159], v[92:95]
	v_mfma_f32_16x16x32_bf16 v[72:75], v[124:127], v[148:151], v[72:75]
	ds_read_b64 v[124:125], v224 offset:18432
	ds_read_b64 v[126:127], v225 offset:18432
	s_waitcnt lgkmcnt(10)
	v_mfma_f32_16x16x32_bf16 v[96:99], v[128:131], v[156:159], v[96:99]
	v_mfma_f32_16x16x32_bf16 v[76:79], v[128:131], v[148:151], v[76:79]
	ds_read_b64 v[128:129], v226 offset:18432
	ds_read_b64 v[130:131], v228 offset:18432
	s_waitcnt lgkmcnt(10)
	v_mfma_f32_16x16x32_bf16 v[104:107], v[164:167], v[156:159], v[104:107]
	v_mfma_f32_16x16x32_bf16 v[80:83], v[164:167], v[148:151], v[80:83]
	ds_read_b64 v[164:165], v229 offset:18432
	ds_read_b64 v[166:167], v240 offset:18432
	s_waitcnt lgkmcnt(10)
	v_mfma_f32_16x16x32_bf16 v[108:111], v[168:171], v[156:159], v[108:111]
	v_mfma_f32_16x16x32_bf16 v[64:67], v[168:171], v[148:151], v[64:67]
	ds_read_b64 v[168:169], v241 offset:18432
	ds_read_b64 v[170:171], v242 offset:18432
	s_waitcnt lgkmcnt(10)
	v_mfma_f32_16x16x32_bf16 v[92:95], v[172:175], v[160:163], v[92:95]
	v_mfma_f32_16x16x32_bf16 v[72:75], v[172:175], v[88:91], v[72:75]
	ds_read_b64 v[172:173], v243 offset:18432
	ds_read_b64 v[174:175], v244 offset:18432
	s_waitcnt lgkmcnt(10)
	v_mfma_f32_16x16x32_bf16 v[96:99], v[120:123], v[160:163], v[96:99]
	v_mfma_f32_16x16x32_bf16 v[76:79], v[120:123], v[88:91], v[76:79]
	ds_read_b64 v[120:121], v245 offset:18432
	ds_read_b64 v[122:123], v246 offset:18432
	s_waitcnt lgkmcnt(10)
	v_mfma_f32_16x16x32_bf16 v[104:107], v[124:127], v[160:163], v[104:107]
	v_mfma_f32_16x16x32_bf16 v[80:83], v[124:127], v[88:91], v[80:83]
	s_waitcnt lgkmcnt(8)
	v_mfma_f32_16x16x32_bf16 v[108:111], v[128:131], v[160:163], v[108:111]
	v_mfma_f32_16x16x32_bf16 v[64:67], v[128:131], v[88:91], v[64:67]
	s_waitcnt lgkmcnt(6)
	v_mfma_f32_16x16x32_bf16 v[92:95], v[164:167], v[116:119], v[92:95]
	v_mfma_f32_16x16x32_bf16 v[72:75], v[164:167], v[100:103], v[72:75]
	s_waitcnt lgkmcnt(4)
	v_mfma_f32_16x16x32_bf16 v[96:99], v[168:171], v[116:119], v[96:99]
	v_mfma_f32_16x16x32_bf16 v[76:79], v[168:171], v[100:103], v[76:79]
	s_waitcnt lgkmcnt(2)
	v_mfma_f32_16x16x32_bf16 v[104:107], v[172:175], v[116:119], v[104:107]
	v_mfma_f32_16x16x32_bf16 v[80:83], v[172:175], v[100:103], v[80:83]
	s_waitcnt lgkmcnt(0)
	v_mfma_f32_16x16x32_bf16 v[108:111], v[120:123], v[116:119], v[108:111]
	v_mfma_f32_16x16x32_bf16 v[64:67], v[120:123], v[100:103], v[64:67]
	s_branch .LBB0_312

.LBB0_318:
	v_max_f32_e32 v32, v27, v27
	v_max_f32_e32 v34, v26, v26
	v_max_f32_e32 v32, v34, v32
	v_max_f32_e32 v34, v31, v31
	v_max_f32_e32 v35, v30, v30
	v_max_f32_e32 v34, v35, v34
	v_max3_f32 v32, v24, v25, v32
	v_max3_f32 v34, v28, v29, v34
	s_mov_b32 s20, 0xf149f2ca
	v_max3_f32 v32, v32, s20, v34
	v_max_f32_e32 v34, v39, v39
	v_max_f32_e32 v35, v38, v38
	v_max_f32_e32 v34, v35, v34
	v_max_f32_e32 v35, v43, v43
	v_max_f32_e32 v88, v42, v42
	v_max_f32_e32 v35, v88, v35
	v_max3_f32 v34, v36, v37, v34
	v_max3_f32 v35, v40, v41, v35
	v_max3_f32 v32, v32, v34, v35
	v_max_f32_e32 v34, v47, v47
	v_max_f32_e32 v35, v46, v46
	v_max_f32_e32 v34, v35, v34
	v_max_f32_e32 v35, v63, v63
	v_max_f32_e32 v88, v62, v62
	v_max_f32_e32 v35, v88, v35
	v_max3_f32 v34, v44, v45, v34
	v_max3_f32 v35, v60, v61, v35
	v_max3_f32 v32, v32, v34, v35
	v_max_f32_e32 v34, v59, v59
	v_max_f32_e32 v35, v58, v58
	v_max_f32_e32 v34, v35, v34
	v_max_f32_e32 v35, v71, v71
	v_max_f32_e32 v88, v70, v70
	v_max_f32_e32 v35, v88, v35
	v_max3_f32 v34, v56, v57, v34
	v_max3_f32 v35, v68, v69, v35
	v_max3_f32 v32, v32, v34, v35
	ds_bpermute_b32 v34, v198, v32
	s_waitcnt lgkmcnt(0)
	v_max_f32_e32 v34, v34, v34
	v_max_f32_e32 v32, v32, v34
	ds_bpermute_b32 v34, v199, v32
	s_waitcnt lgkmcnt(0)
	v_max3_f32 v34, v201, v32, v34
	v_mul_f32_e32 v32, 0xbfb8aa3b, v34
	v_fmamk_f32 v24, v24, 0x3fb8aa3b, v32
	v_exp_f32_e32 v24, v24
	v_fmamk_f32 v25, v25, 0x3fb8aa3b, v32
	v_exp_f32_e32 v25, v25
	v_fmamk_f32 v26, v26, 0x3fb8aa3b, v32
	v_exp_f32_e32 v26, v26
	v_fmamk_f32 v27, v27, 0x3fb8aa3b, v32
	v_exp_f32_e32 v27, v27
	v_fmamk_f32 v28, v28, 0x3fb8aa3b, v32
	v_add_f32_e32 v88, 0, v24
	v_exp_f32_e32 v28, v28
	v_fmamk_f32 v29, v29, 0x3fb8aa3b, v32
	v_add_f32_e32 v88, v25, v88
	v_exp_f32_e32 v29, v29
	v_fmamk_f32 v30, v30, 0x3fb8aa3b, v32
	v_add_f32_e32 v88, v26, v88
	v_exp_f32_e32 v30, v30
	v_fmamk_f32 v31, v31, 0x3fb8aa3b, v32
	v_add_f32_e32 v88, v27, v88
	v_exp_f32_e32 v31, v31
	v_fmamk_f32 v36, v36, 0x3fb8aa3b, v32
	v_add_f32_e32 v88, v28, v88
	v_exp_f32_e32 v36, v36
	v_fmamk_f32 v37, v37, 0x3fb8aa3b, v32
	v_add_f32_e32 v88, v29, v88
	v_exp_f32_e32 v37, v37
	v_fmamk_f32 v38, v38, 0x3fb8aa3b, v32
	v_add_f32_e32 v88, v30, v88
	v_exp_f32_e32 v38, v38
	v_fmamk_f32 v39, v39, 0x3fb8aa3b, v32
	v_add_f32_e32 v88, v31, v88
	v_exp_f32_e32 v39, v39
	v_fmamk_f32 v40, v40, 0x3fb8aa3b, v32
	v_add_f32_e32 v88, v36, v88
	v_exp_f32_e32 v40, v40
	v_fmamk_f32 v41, v41, 0x3fb8aa3b, v32
	v_add_f32_e32 v88, v37, v88
	v_exp_f32_e32 v41, v41
	v_fmamk_f32 v42, v42, 0x3fb8aa3b, v32
	v_add_f32_e32 v88, v38, v88
	v_exp_f32_e32 v42, v42
	v_fmamk_f32 v43, v43, 0x3fb8aa3b, v32
	v_add_f32_e32 v88, v39, v88
	v_exp_f32_e32 v43, v43
	v_fmamk_f32 v44, v44, 0x3fb8aa3b, v32
	v_add_f32_e32 v88, v40, v88
	v_exp_f32_e32 v44, v44
	v_fmamk_f32 v45, v45, 0x3fb8aa3b, v32
	v_add_f32_e32 v88, v41, v88
	v_exp_f32_e32 v45, v45
	v_fmamk_f32 v46, v46, 0x3fb8aa3b, v32
	v_add_f32_e32 v88, v42, v88
	v_exp_f32_e32 v46, v46
	v_fmamk_f32 v47, v47, 0x3fb8aa3b, v32
	v_add_f32_e32 v88, v43, v88
	v_exp_f32_e32 v47, v47
	v_fmamk_f32 v60, v60, 0x3fb8aa3b, v32
	v_add_f32_e32 v88, v44, v88
	v_exp_f32_e32 v60, v60
	v_fmamk_f32 v61, v61, 0x3fb8aa3b, v32
	v_add_f32_e32 v88, v45, v88
	v_exp_f32_e32 v61, v61
	v_fmamk_f32 v62, v62, 0x3fb8aa3b, v32
	v_add_f32_e32 v88, v46, v88
	v_exp_f32_e32 v62, v62
	v_fmamk_f32 v63, v63, 0x3fb8aa3b, v32
	v_add_f32_e32 v88, v47, v88
	v_exp_f32_e32 v63, v63
	v_fmamk_f32 v56, v56, 0x3fb8aa3b, v32
	v_add_f32_e32 v88, v60, v88
	v_exp_f32_e32 v56, v56
	v_fmamk_f32 v57, v57, 0x3fb8aa3b, v32
	v_add_f32_e32 v88, v61, v88
	v_exp_f32_e32 v57, v57
	v_fmamk_f32 v58, v58, 0x3fb8aa3b, v32
	v_add_f32_e32 v88, v62, v88
	v_exp_f32_e32 v58, v58
	v_fmamk_f32 v59, v59, 0x3fb8aa3b, v32
	v_add_f32_e32 v88, v63, v88
	v_exp_f32_e32 v59, v59
	v_fmamk_f32 v68, v68, 0x3fb8aa3b, v32
	v_add_f32_e32 v88, v56, v88
	v_exp_f32_e32 v68, v68
	v_fmamk_f32 v69, v69, 0x3fb8aa3b, v32
	v_add_f32_e32 v88, v57, v88
	v_exp_f32_e32 v69, v69
	v_fmamk_f32 v70, v70, 0x3fb8aa3b, v32
	v_sub_f32_e32 v35, v201, v34
	v_add_f32_e32 v88, v58, v88
	v_exp_f32_e32 v70, v70
	v_fmac_f32_e32 v32, 0x3fb8aa3b, v71
	v_mul_f32_e32 v35, 0x3fb8aa3b, v35
	v_add_f32_e32 v88, v59, v88
	v_exp_f32_e32 v71, v32
	v_add_f32_e32 v88, v68, v88
	v_exp_f32_e32 v32, v35
	v_add_f32_e32 v35, v69, v88
	v_add_f32_e32 v35, v70, v35
	v_add_f32_e32 v35, v71, v35
	v_fmac_f32_e32 v35, v200, v32
	v_pk_mul_f32 v[74:75], v[74:75], v[32:33] op_sel_hi:[1,0]
	v_pk_mul_f32 v[72:73], v[72:73], v[32:33] op_sel_hi:[1,0]
	v_pk_mul_f32 v[78:79], v[78:79], v[32:33] op_sel_hi:[1,0]
	v_pk_mul_f32 v[76:77], v[76:77], v[32:33] op_sel_hi:[1,0]
	v_pk_mul_f32 v[82:83], v[82:83], v[32:33] op_sel_hi:[1,0]
	v_pk_mul_f32 v[80:81], v[80:81], v[32:33] op_sel_hi:[1,0]
	v_pk_mul_f32 v[66:67], v[66:67], v[32:33] op_sel_hi:[1,0]
	v_pk_mul_f32 v[64:65], v[64:65], v[32:33] op_sel_hi:[1,0]
	v_cvt_pk_bf16_f32 v144, v24, v25
	v_cvt_pk_bf16_f32 v145, v26, v27
	v_cvt_pk_bf16_f32 v146, v28, v29
	v_cvt_pk_bf16_f32 v147, v30, v31
	v_cvt_pk_bf16_f32 v148, v36, v37
	v_cvt_pk_bf16_f32 v149, v38, v39
	v_cvt_pk_bf16_f32 v150, v40, v41
	v_cvt_pk_bf16_f32 v151, v42, v43
	v_cvt_pk_bf16_f32 v88, v44, v45
	v_cvt_pk_bf16_f32 v89, v46, v47
	v_cvt_pk_bf16_f32 v90, v60, v61
	v_cvt_pk_bf16_f32 v91, v62, v63
	v_cvt_pk_bf16_f32 v100, v56, v57
	v_cvt_pk_bf16_f32 v101, v58, v59
	v_cvt_pk_bf16_f32 v102, v68, v69
	v_cvt_pk_bf16_f32 v103, v70, v71
	v_mov_b32_e32 v200, v35
	v_mov_b32_e32 v201, v34
	s_and_b64 vcc, exec, s[96:97]
	s_cbranch_vccz .Lpv_fast
	ds_read_b64 v[164:165], v202 offset:18432
	ds_read_b64 v[166:167], v203 offset:18432
	s_and_b64 vcc, exec, s[96:97]
	s_cbranch_vccz .LBB0_281

.LBB0_412:
	s_lshl_b32 s2, s11, 4
	s_or_b32 s2, s2, s12
	s_ashr_i32 s3, s2, 31
	v_add_u32_e32 v32, s13, v35
	s_lshl_b64 s[4:5], s[2:3], 15
	v_readlane_b32 s6, v255, 15
	v_lshlrev_b32_e32 v52, 2, v68
	v_cmp_lt_i32_e64 s[46:47], -1, v32
	v_readlane_b32 s7, v255, 16
	s_add_u32 s4, s6, s4
	v_and_b32_e32 v72, 0x7c, v52
	v_and_b32_e32 v110, 0xffffff80, v52
	v_cndmask_b32_e64 v108, 0, v32, s[46:47]
	s_addc_u32 s5, s7, s5
	v_lshlrev_b32_e32 v32, 2, v72
	v_add_u32_e32 v112, 0x800, v110
	v_add_u32_e32 v114, 0x1000, v110
	v_add_u32_e32 v116, 0x1800, v110
	v_lshl_add_u64 v[60:61], s[4:5], 0, v[32:33]
	v_ashrrev_i32_e32 v111, 31, v110
	v_ashrrev_i32_e32 v113, 31, v112
	v_ashrrev_i32_e32 v115, 31, v114
	v_ashrrev_i32_e32 v117, 31, v116
	v_lshl_add_u64 v[52:53], v[110:111], 2, v[60:61]
	v_lshl_add_u64 v[56:57], v[112:113], 2, v[60:61]
	v_lshl_add_u64 v[62:63], v[114:115], 2, v[60:61]
	v_lshl_add_u64 v[64:65], v[116:117], 2, v[60:61]
	global_load_dwordx4 v[52:55], v[52:53], off
	s_nop 0
	global_load_dwordx4 v[56:59], v[56:57], off
	s_nop 0
	global_load_dwordx4 v[60:63], v[62:63], off
	s_nop 0
	global_load_dwordx4 v[64:67], v[64:65], off
	s_ashr_i32 s4, s10, 3
	s_and_b32 s3, s4, -16
	v_lshl_add_u64 v[118:119], s[6:7], 0, v[32:33]
	s_or_b32 s24, s4, 15
	v_ashrrev_i32_e32 v32, 5, v68
	s_movk_i32 s4, 0x110
	v_mul_lo_u32 v78, v32, s4
	v_add_u32_e32 v32, 0x200, v68
	v_ashrrev_i32_e32 v32, 5, v32
	v_readlane_b32 s25, v254, 39
	v_mul_lo_u32 v79, v32, s4
	v_add_u32_e32 v32, 0x400, v68
	v_lshl_add_u32 v142, v69, 1, s25
	v_lshrrev_b32_e32 v69, 2, v68
	v_ashrrev_i32_e32 v32, 5, v32
	v_and_b32_e32 v141, 12, v69
	v_mul_lo_u32 v80, v32, s4
	v_add_u32_e32 v32, 0x600, v68
	v_ashrrev_i32_e32 v32, 5, v32
	v_or_b32_e32 v83, 0x41, v141
	v_mul_lo_u32 v81, v32, s4
	v_or_b32_e32 v32, 17, v141
	v_cmp_gt_i32_e64 s[80:81], v83, v35
	v_or_b32_e32 v83, 0x51, v141
	v_cmp_gt_i32_e64 s[52:53], v32, v35
	v_or_b32_e32 v32, 3, v141
	v_cmp_gt_i32_e64 s[84:85], v83, v35
	v_or_b32_e32 v83, 0x43, v141
	v_cmp_gt_i32_e64 s[56:57], v32, v35
	v_or_b32_e32 v32, 19, v141
	v_cmp_gt_i32_e64 s[88:89], v83, v35
	v_or_b32_e32 v83, 0x53, v141
	v_cmp_gt_i32_e64 s[60:61], v32, v35
	v_or_b32_e32 v32, 33, v141
	v_cmp_gt_i32_e64 s[92:93], v83, v35
	v_or_b32_e32 v83, 0x61, v141
	v_readlane_b32 s5, v254, 40
	v_cmp_gt_i32_e64 s[64:65], v32, v35
	v_or_b32_e32 v32, 49, v141
	v_or_b32_e32 v86, 0x42, v141
	v_cmp_gt_i32_e64 s[96:97], v83, v35
	v_or_b32_e32 v83, 0x71, v141
	v_lshl_add_u32 v76, v72, 1, s5
	v_or_b32_e32 v72, 2, v141
	v_cmp_gt_i32_e64 s[68:69], v32, v35
	v_or_b32_e32 v32, 35, v141
	v_or_b32_e32 v74, 34, v141
	v_cmp_gt_i32_e64 s[90:91], v86, v35
	v_or_b32_e32 v86, 0x52, v141
	v_cmp_gt_i32_e64 s[6:7], v83, v35
	v_or_b32_e32 v83, 0x63, v141
	v_or_b32_e32 v88, 0x62, v141
	v_or_b32_e32 v69, 16, v141
	v_cmp_gt_i32_e64 s[58:59], v72, v35
	v_or_b32_e32 v72, 18, v141
	v_or_b32_e32 v75, 32, v141
	v_or_b32_e32 v82, 48, v141
	v_cmp_gt_i32_e64 s[72:73], v32, v35
	v_cmp_gt_i32_e64 s[74:75], v74, v35
	v_or_b32_e32 v32, 51, v141
	v_or_b32_e32 v74, 50, v141
	v_or_b32_e32 v84, 64, v141
	v_or_b32_e32 v85, 0x50, v141
	v_cmp_gt_i32_e64 s[94:95], v86, v35
	v_or_b32_e32 v86, 0x60, v141
	v_or_b32_e32 v87, 0x70, v141
	v_cmp_gt_i32_e64 s[10:11], v83, v35
	v_cmp_gt_i32_e64 s[12:13], v88, v35
	v_or_b32_e32 v83, 0x73, v141
	v_or_b32_e32 v88, 0x72, v141
	v_add_u32_e32 v70, s5, v70
	v_lshl_add_u32 v77, v35, 1, s25
	v_cmp_gt_i32_e64 s[48:49], v141, v35
	v_cmp_lt_i32_e64 s[50:51], v141, v35
	v_cmp_gt_i32_e64 s[54:55], v69, v35
	v_cmp_gt_i32_e64 s[62:63], v72, v35
	v_add_u32_e32 v73, s25, v71
	v_cmp_gt_i32_e64 s[66:67], v75, v35
	v_cmp_gt_i32_e64 s[70:71], v82, v35
	v_cmp_gt_i32_e64 s[76:77], v32, v35
	v_cmp_gt_i32_e64 s[78:79], v74, v35
	v_cmp_gt_i32_e64 s[82:83], v84, v35
	v_cmp_gt_i32_e64 s[86:87], v85, v35
	v_cmp_gt_i32_e64 s[4:5], v86, v35
	v_cmp_gt_i32_e64 s[8:9], v87, v35
	v_cmp_gt_i32_e64 s[14:15], v83, v35
	v_cmp_gt_i32_e64 s[16:17], v88, v35
	v_lshlrev_b32_e32 v35, 1, v86
	v_lshlrev_b32_e32 v83, 1, v87
	v_add_u32_e32 v150, v73, v83
	v_add_u32_e32 v88, s25, v35
	v_add_u32_e32 v83, s25, v83
	s_lshl_b32 s25, s38, 6
	s_add_i32 s25, s25, 0
	v_ashrrev_i32_e32 v109, 31, v108
	s_add_i32 s25, s25, 0x1a800
	v_lshlrev_b32_e32 v32, 1, v82
	v_add_u32_e32 v149, v73, v35
	v_mul_u32_u24_e32 v92, 0x110, v82
	v_lshl_add_u32 v155, v82, 2, 0
	v_bfe_u32 v82, v68, 4, 2
	v_lshl_add_u32 v159, v34, 2, s25
	v_lshlrev_b64 v[34:35], 12, v[108:109]
	v_mov_b32_e32 v68, 0x1010000
	v_mad_i64_i32 v[34:35], s[38:39], s29, v68, v[34:35]
	v_readlane_b32 s38, v255, 48
	v_lshlrev_b32_e32 v72, 1, v69
	v_lshlrev_b32_e32 v74, 1, v75
	v_mul_u32_u24_e32 v90, 0x110, v69
	v_mul_u32_u24_e32 v91, 0x110, v75
	v_lshl_add_u32 v156, v75, 2, 0
	v_lshl_add_u32 v157, v69, 2, 0
	s_lshl_b32 s25, s28, 5
	v_readlane_b32 s36, v255, 46
	v_lshl_add_u64 v[68:69], v[34:35], 0, v[32:33]
	v_readlane_b32 s39, v255, 49
	v_mov_b32_e32 v75, v33
	v_lshl_add_u32 v143, v141, 1, v73
	v_add_u32_e32 v144, v73, v72
	v_add_u32_e32 v145, v73, v74
	v_add_u32_e32 v146, v73, v32
	v_lshl_add_u32 v147, v84, 1, v73
	v_lshl_add_u32 v148, v85, 1, v73
	s_add_u32 s42, s36, s25
	v_readlane_b32 s25, v255, 47
	v_lshl_add_u64 v[120:121], s[38:39], 0, v[68:69]
	v_lshl_add_u64 v[68:69], v[34:35], 0, v[74:75]
	v_mov_b32_e32 v73, v33
	v_lshlrev_b32_e32 v32, 3, v82
	s_addc_u32 s43, s25, 0
	s_add_i32 s44, s2, 1
	v_lshl_add_u64 v[122:123], s[38:39], 0, v[68:69]
	v_lshl_add_u64 v[68:69], v[34:35], 0, v[72:73]
	v_or_b32_e32 v34, v34, v32
	s_movk_i32 s2, 0x2600
	v_lshl_add_u64 v[124:125], s[38:39], 0, v[68:69]
	v_lshl_add_u64 v[126:127], s[38:39], 0, v[34:35]
	v_mad_i64_i32 v[34:35], s[38:39], v108, s2, 0
	v_mad_i64_i32 v[34:35], s[38:39], s29, v238, v[34:35]
	s_lshl_b32 s2, s28, 9
	v_readlane_b32 s38, v255, 50
	v_mul_u32_u24_e32 v89, 0x110, v141
	v_or_b32_e32 v34, v34, v32
	v_readlane_b32 s39, v255, 51
	v_writelane_b32 v255, s2, 63
	s_mov_b32 s1, 0
	s_mul_i32 s33, s3, 0x110
	s_mulk_i32 s24, 0x110
	v_lshl_add_u32 v151, v87, 2, 0
	v_lshl_add_u32 v152, v86, 2, 0
	v_lshl_add_u32 v153, v85, 2, 0
	v_lshl_add_u32 v154, v84, 2, 0
	v_lshl_add_u32 v158, v82, 4, 0
	v_lshl_add_u64 v[128:129], s[38:39], 0, v[34:35]
	v_mov_b32_e32 v171, 0
	v_add_u32_e32 v160, v76, v78
	v_add_u32_e32 v161, v76, v79
	v_add_u32_e32 v162, v76, v80
	v_add_u32_e32 v163, v76, v81
	v_add_u32_e32 v164, v88, v71
	v_add_u32_e32 v165, v83, v71
	v_add_u32_e32 v166, v70, v71
	v_add_u32_e32 v167, v77, v90
	v_add_u32_e32 v168, v77, v91
	v_add_u32_e32 v169, v77, v92
	v_add_u32_e32 v170, v77, v89
	s_add_i32 s2, s2, s3
	s_lshl_b32 s36, s28, 10
	v_readlane_b32 s25, v255, 52
	s_branch .LBB0_414

.LBB0_414:
	v_mov_b32_e32 v35, 0
	v_mov_b32_e32 v34, 0
	v_mov_b32_e32 v69, 0
	v_mov_b32_e32 v68, 0
	v_mov_b32_e32 v71, 0
	v_mov_b32_e32 v70, 0
	v_mov_b32_e32 v73, 0
	v_mov_b32_e32 v72, 0
	v_mov_b32_e32 v75, 0
	v_mov_b32_e32 v74, 0
	v_mov_b32_e32 v77, 0
	v_mov_b32_e32 v76, 0
	v_mov_b32_e32 v79, 0
	v_mov_b32_e32 v78, 0
	v_mov_b32_e32 v81, 0
	v_mov_b32_e32 v80, 0
	s_waitcnt lgkmcnt(0)
	s_barrier
	s_mov_b64 vcc, exec
	v_readlane_b32 s28, v255, 59
	v_readlane_b32 s29, v255, 60
	s_and_b64 s[28:29], vcc, s[28:29]
	s_mov_b64 exec, s[28:29]
	s_cbranch_execz .LBB0_422
	s_ashr_i32 s3, s2, 31
	s_lshl_b64 s[28:29], s[2:3], 2
	v_readlane_b32 s38, v255, 38
	v_readlane_b32 s39, v255, 39
	s_add_u32 s38, s38, s28
	s_addc_u32 s39, s39, s29
	s_nop 2
	global_load_dwordx4 v[72:75], v33, s[38:39] offset:32
	global_load_dwordx4 v[68:71], v33, s[38:39] offset:48
	global_load_dwordx4 v[76:79], v33, s[38:39]
	global_load_dwordx4 v[80:83], v33, s[38:39] offset:16
	s_add_u32 s38, s25, s28
	v_readlane_b32 s28, v255, 37
	s_addc_u32 s39, s28, s29
	s_mov_b64 s[28:29], exec
	v_readlane_b32 s40, v255, 53
	v_readlane_b32 s41, v255, 54
	s_and_b64 s[40:41], s[28:29], s[40:41]
	s_mov_b64 exec, s[40:41]
	s_cbranch_execz .LBB0_417
	v_lshl_add_u64 v[34:35], s[2:3], 1, v[100:101]
	global_load_dwordx4 v[84:87], v[34:35], off offset:16
	global_load_dwordx4 v[88:91], v[34:35], off
	global_load_dwordx4 v[92:95], v33, s[38:39] offset:48
	global_load_dwordx4 v[96:99], v33, s[38:39] offset:16
	global_load_dwordx4 v[130:133], v33, s[38:39] offset:32
	global_load_dwordx4 v[134:137], v33, s[38:39]
	s_waitcnt vmcnt(4)
	v_lshlrev_b32_e32 v34, 16, v88
	v_and_b32_e32 v35, 0xffff0000, v88
	s_waitcnt vmcnt(0)
	v_pk_fma_f32 v[76:77], v[134:135], v[34:35], v[76:77]
	v_lshlrev_b32_e32 v34, 16, v84
	v_and_b32_e32 v35, 0xffff0000, v84
	v_pk_fma_f32 v[72:73], v[130:131], v[34:35], v[72:73]
	v_lshlrev_b32_e32 v34, 16, v89
	v_and_b32_e32 v35, 0xffff0000, v89
	v_pk_fma_f32 v[78:79], v[136:137], v[34:35], v[78:79]
	v_lshlrev_b32_e32 v34, 16, v85
	v_and_b32_e32 v35, 0xffff0000, v85
	v_pk_fma_f32 v[74:75], v[132:133], v[34:35], v[74:75]
	v_lshlrev_b32_e32 v34, 16, v90
	v_and_b32_e32 v35, 0xffff0000, v90
	v_pk_fma_f32 v[80:81], v[96:97], v[34:35], v[80:81]
	v_lshlrev_b32_e32 v34, 16, v86
	v_and_b32_e32 v35, 0xffff0000, v86
	v_pk_fma_f32 v[68:69], v[92:93], v[34:35], v[68:69]
	v_lshlrev_b32_e32 v34, 16, v91
	v_and_b32_e32 v35, 0xffff0000, v91
	v_pk_fma_f32 v[82:83], v[98:99], v[34:35], v[82:83]
	v_lshlrev_b32_e32 v34, 16, v87
	v_and_b32_e32 v35, 0xffff0000, v87
	v_pk_fma_f32 v[70:71], v[94:95], v[34:35], v[70:71]
.LBB0_417:
	s_or_b64 exec, exec, s[28:29]
	s_mov_b64 s[28:29], exec
	v_readlane_b32 s40, v255, 55
	v_readlane_b32 s41, v255, 56
	s_and_b64 s[40:41], s[28:29], s[40:41]
	s_mov_b64 exec, s[40:41]
	s_cbranch_execz .LBB0_419
	v_lshl_add_u64 v[34:35], s[2:3], 1, v[102:103]
	s_add_u32 s40, s38, 0x1800
	global_load_dwordx4 v[84:87], v[34:35], off offset:16
	global_load_dwordx4 v[88:91], v[34:35], off
	s_addc_u32 s41, s39, 0
	global_load_dwordx4 v[92:95], v33, s[40:41] offset:48
	global_load_dwordx4 v[96:99], v33, s[40:41] offset:16
	global_load_dwordx4 v[130:133], v33, s[40:41] offset:32
	global_load_dwordx4 v[134:137], v231, s[38:39] offset:2048
	s_waitcnt vmcnt(4)
	v_lshlrev_b32_e32 v34, 16, v88
	v_and_b32_e32 v35, 0xffff0000, v88
	s_waitcnt vmcnt(0)
	v_pk_fma_f32 v[76:77], v[134:135], v[34:35], v[76:77]
	v_lshlrev_b32_e32 v34, 16, v84
	v_and_b32_e32 v35, 0xffff0000, v84
	v_pk_fma_f32 v[72:73], v[130:131], v[34:35], v[72:73]
	v_lshlrev_b32_e32 v34, 16, v89
	v_and_b32_e32 v35, 0xffff0000, v89
	v_pk_fma_f32 v[78:79], v[136:137], v[34:35], v[78:79]
	v_lshlrev_b32_e32 v34, 16, v85
	v_and_b32_e32 v35, 0xffff0000, v85
	v_pk_fma_f32 v[74:75], v[132:133], v[34:35], v[74:75]
	v_lshlrev_b32_e32 v34, 16, v90
	v_and_b32_e32 v35, 0xffff0000, v90
	v_pk_fma_f32 v[80:81], v[96:97], v[34:35], v[80:81]
	v_lshlrev_b32_e32 v34, 16, v86
	v_and_b32_e32 v35, 0xffff0000, v86
	v_pk_fma_f32 v[68:69], v[92:93], v[34:35], v[68:69]
	v_lshlrev_b32_e32 v34, 16, v91
	v_and_b32_e32 v35, 0xffff0000, v91
	v_pk_fma_f32 v[82:83], v[98:99], v[34:35], v[82:83]
	v_lshlrev_b32_e32 v34, 16, v87
	v_and_b32_e32 v35, 0xffff0000, v87
	v_pk_fma_f32 v[70:71], v[94:95], v[34:35], v[70:71]
.LBB0_419:
	s_or_b64 exec, exec, s[28:29]
	s_mov_b64 s[28:29], exec
	v_readlane_b32 s40, v255, 57
	v_readlane_b32 s41, v255, 58
	s_and_b64 s[40:41], s[28:29], s[40:41]
	s_mov_b64 exec, s[40:41]
	s_cbranch_execz .LBB0_421
	v_lshl_add_u64 v[34:35], s[2:3], 1, v[104:105]
	s_add_u32 s40, s38, 0x3000
	global_load_dwordx4 v[84:87], v[34:35], off offset:16
	global_load_dwordx4 v[88:91], v[34:35], off
	s_addc_u32 s41, s39, 0
	global_load_dwordx4 v[92:95], v33, s[40:41] offset:48
	global_load_dwordx4 v[96:99], v33, s[40:41] offset:16
	global_load_dwordx4 v[130:133], v33, s[40:41] offset:32
	global_load_dwordx4 v[134:137], v232, s[38:39]
	s_waitcnt vmcnt(4)
	v_lshlrev_b32_e32 v34, 16, v88
	v_and_b32_e32 v35, 0xffff0000, v88
	s_waitcnt vmcnt(0)
	v_pk_fma_f32 v[76:77], v[134:135], v[34:35], v[76:77]
	v_lshlrev_b32_e32 v34, 16, v84
	v_and_b32_e32 v35, 0xffff0000, v84
	v_pk_fma_f32 v[72:73], v[130:131], v[34:35], v[72:73]
	v_lshlrev_b32_e32 v34, 16, v89
	v_and_b32_e32 v35, 0xffff0000, v89
	v_pk_fma_f32 v[78:79], v[136:137], v[34:35], v[78:79]
	v_lshlrev_b32_e32 v34, 16, v85
	v_and_b32_e32 v35, 0xffff0000, v85
	v_pk_fma_f32 v[74:75], v[132:133], v[34:35], v[74:75]
	v_lshlrev_b32_e32 v34, 16, v90
	v_and_b32_e32 v35, 0xffff0000, v90
	v_pk_fma_f32 v[80:81], v[96:97], v[34:35], v[80:81]
	v_lshlrev_b32_e32 v34, 16, v86
	v_and_b32_e32 v35, 0xffff0000, v86
	v_pk_fma_f32 v[68:69], v[92:93], v[34:35], v[68:69]
	v_lshlrev_b32_e32 v34, 16, v91
	v_and_b32_e32 v35, 0xffff0000, v91
	v_pk_fma_f32 v[82:83], v[98:99], v[34:35], v[82:83]
	v_lshlrev_b32_e32 v34, 16, v87
	v_and_b32_e32 v35, 0xffff0000, v87
	v_pk_fma_f32 v[70:71], v[94:95], v[34:35], v[70:71]
.LBB0_421:
	s_or_b64 exec, exec, s[28:29]
	v_lshl_add_u64 v[34:35], s[2:3], 1, v[106:107]
	global_load_dwordx4 v[84:87], v[34:35], off
	global_load_dwordx4 v[88:91], v[34:35], off offset:16
	s_add_u32 s28, s38, 0x4800
	global_load_dwordx4 v[92:95], v233, s[38:39] offset:2048
	s_addc_u32 s29, s39, 0
	global_load_dwordx4 v[96:99], v33, s[28:29] offset:16
	global_load_dwordx4 v[130:133], v33, s[28:29] offset:32
	global_load_dwordx4 v[134:137], v33, s[28:29] offset:48
	s_waitcnt vmcnt(5)
	v_lshlrev_b32_e32 v34, 16, v84
	v_and_b32_e32 v35, 0xffff0000, v84
	v_lshlrev_b32_e32 v138, 16, v86
	s_waitcnt vmcnt(3)
	v_pk_fma_f32 v[34:35], v[92:93], v[34:35], v[76:77]
	v_and_b32_e32 v139, 0xffff0000, v86
	v_lshlrev_b32_e32 v86, 16, v87
	v_and_b32_e32 v87, 0xffff0000, v87
	v_lshlrev_b32_e32 v172, 16, v88
	v_and_b32_e32 v173, 0xffff0000, v88
	v_lshlrev_b32_e32 v88, 16, v89
	v_and_b32_e32 v89, 0xffff0000, v89
	v_lshlrev_b32_e32 v174, 16, v90
	v_and_b32_e32 v175, 0xffff0000, v90
	v_lshlrev_b32_e32 v90, 16, v91
	v_and_b32_e32 v91, 0xffff0000, v91
	v_mul_f32_e32 v32, 0xbfb8aa3b, v34
	s_waitcnt vmcnt(2)
	v_pk_fma_f32 v[82:83], v[98:99], v[86:87], v[82:83]
	s_waitcnt vmcnt(1)
	v_pk_fma_f32 v[86:87], v[132:133], v[88:89], v[74:75]
	s_waitcnt vmcnt(0)
	v_pk_fma_f32 v[88:89], v[136:137], v[90:91], v[70:71]
	v_mul_f32_e32 v70, 0xbfb8aa3b, v35
	v_exp_f32_e32 v32, v32
	v_exp_f32_e32 v70, v70
	v_lshlrev_b32_e32 v84, 16, v85
	v_and_b32_e32 v85, 0xffff0000, v85
	v_pk_fma_f32 v[76:77], v[94:95], v[84:85], v[78:79]
	v_pk_fma_f32 v[84:85], v[96:97], v[138:139], v[80:81]
	v_pk_fma_f32 v[72:73], v[130:131], v[172:173], v[72:73]
	v_pk_fma_f32 v[68:69], v[134:135], v[174:175], v[68:69]
	v_mul_f32_e32 v78, 0xbfb8aa3b, v85
	v_mul_f32_e32 v95, 0xbfb8aa3b, v88
	v_add_f32_e32 v32, 1.0, v32
	v_mul_f32_e32 v71, 0xbfb8aa3b, v76
	v_mul_f32_e32 v74, 0xbfb8aa3b, v77
	v_mul_f32_e32 v75, 0xbfb8aa3b, v84
	v_mul_f32_e32 v79, 0xbfb8aa3b, v82
	v_mul_f32_e32 v80, 0xbfb8aa3b, v83
	v_mul_f32_e32 v81, 0xbfb8aa3b, v72
	v_mul_f32_e32 v90, 0xbfb8aa3b, v73
	v_mul_f32_e32 v91, 0xbfb8aa3b, v86
	v_mul_f32_e32 v92, 0xbfb8aa3b, v87
	v_mul_f32_e32 v93, 0xbfb8aa3b, v68
	v_mul_f32_e32 v94, 0xbfb8aa3b, v69
	v_exp_f32_e32 v78, v78
	v_exp_f32_e32 v130, v95
	v_add_f32_e32 v95, 1.0, v70
	v_rcp_f32_e32 v70, v32
	v_mul_f32_e32 v32, 0xbfb8aa3b, v89
	v_exp_f32_e32 v71, v71
	v_exp_f32_e32 v74, v74
	v_exp_f32_e32 v75, v75
	v_exp_f32_e32 v79, v79
	v_exp_f32_e32 v80, v80
	v_exp_f32_e32 v81, v81
	v_exp_f32_e32 v90, v90
	v_exp_f32_e32 v91, v91
	v_exp_f32_e32 v92, v92
	v_exp_f32_e32 v93, v93
	v_exp_f32_e32 v94, v94
	v_exp_f32_e32 v32, v32
	v_add_f32_e32 v78, 1.0, v78
	v_add_f32_e32 v96, 1.0, v71
	v_add_f32_e32 v97, 1.0, v74
	v_add_f32_e32 v98, 1.0, v75
	v_add_f32_e32 v79, 1.0, v79
	v_add_f32_e32 v80, 1.0, v80
	v_add_f32_e32 v81, 1.0, v81
	v_add_f32_e32 v99, 1.0, v90
	v_add_f32_e32 v131, 1.0, v91
	v_add_f32_e32 v132, 1.0, v92
	v_add_f32_e32 v133, 1.0, v93
	v_add_f32_e32 v134, 1.0, v94
	v_rcp_f32_e32 v91, v78
	v_add_f32_e32 v78, 1.0, v130
	v_add_f32_e32 v32, 1.0, v32
	v_rcp_f32_e32 v71, v95
	v_rcp_f32_e32 v74, v96
	v_rcp_f32_e32 v75, v97
	v_rcp_f32_e32 v90, v98
	v_rcp_f32_e32 v92, v79
	v_rcp_f32_e32 v93, v80
	v_rcp_f32_e32 v94, v81
	v_rcp_f32_e32 v95, v99
	v_rcp_f32_e32 v96, v131
	v_rcp_f32_e32 v97, v132
	v_rcp_f32_e32 v98, v133
	v_rcp_f32_e32 v99, v134
	v_rcp_f32_e32 v130, v78
	v_rcp_f32_e32 v131, v32
	v_pk_mul_f32 v[80:81], v[34:35], v[70:71]
	v_pk_mul_f32 v[78:79], v[76:77], v[74:75]
	v_pk_mul_f32 v[76:77], v[84:85], v[90:91]
	v_pk_mul_f32 v[74:75], v[82:83], v[92:93]
	v_pk_mul_f32 v[72:73], v[72:73], v[94:95]
	v_pk_mul_f32 v[70:71], v[86:87], v[96:97]
	v_pk_mul_f32 v[68:69], v[68:69], v[98:99]
	v_pk_mul_f32 v[34:35], v[88:89], v[130:131]
.LBB0_422:
	s_or_b64 exec, exec, vcc
	v_cvt_pk_bf16_f32 v32, v80, s0
	v_add_u32_e32 v80, s33, v142
	ds_write_b16 v80, v32
	v_cvt_pk_bf16_f32 v32, v81, s0
	ds_write_b16 v80, v32 offset:272
	v_cvt_pk_bf16_f32 v32, v78, s0
	ds_write_b16 v80, v32 offset:544
	v_cvt_pk_bf16_f32 v32, v79, s0
	ds_write_b16 v80, v32 offset:816
	v_cvt_pk_bf16_f32 v32, v76, s0
	ds_write_b16 v80, v32 offset:1088
	v_cvt_pk_bf16_f32 v32, v77, s0
	ds_write_b16 v80, v32 offset:1360
	v_cvt_pk_bf16_f32 v32, v74, s0
	ds_write_b16 v80, v32 offset:1632
	v_cvt_pk_bf16_f32 v32, v75, s0
	ds_write_b16 v80, v32 offset:1904
	v_cvt_pk_bf16_f32 v32, v72, s0
	ds_write_b16 v80, v32 offset:2176
	v_cvt_pk_bf16_f32 v32, v73, s0
	ds_write_b16 v80, v32 offset:2448
	v_cvt_pk_bf16_f32 v32, v70, s0
	ds_write_b16 v80, v32 offset:2720
	v_cvt_pk_bf16_f32 v32, v71, s0
	ds_write_b16 v80, v32 offset:2992
	v_cvt_pk_bf16_f32 v32, v68, s0
	ds_write_b16 v80, v32 offset:3264
	v_cvt_pk_bf16_f32 v32, v69, s0
	ds_write_b16 v80, v32 offset:3536
	v_cvt_pk_bf16_f32 v32, v34, s0
	ds_write_b16 v80, v32 offset:3808
	v_cvt_pk_bf16_f32 v32, v35, s0
	v_add_u32_e32 v34, s24, v142
	ds_write_b16 v34, v32
	s_waitcnt vmcnt(3)
	v_cvt_pk_bf16_f32 v34, v52, v53
	v_cvt_pk_bf16_f32 v35, v54, v55
	ds_write_b64 v160, v[34:35]
	s_waitcnt vmcnt(2)
	v_cvt_pk_bf16_f32 v34, v56, v57
	v_cvt_pk_bf16_f32 v35, v58, v59
	ds_write_b64 v161, v[34:35]
	s_waitcnt vmcnt(1)
	v_cvt_pk_bf16_f32 v34, v60, v61
	v_cvt_pk_bf16_f32 v35, v62, v63
	ds_write_b64 v162, v[34:35]
	s_waitcnt vmcnt(0)
	v_cvt_pk_bf16_f32 v34, v64, v65
	v_cvt_pk_bf16_f32 v35, v66, v67
	ds_write_b64 v163, v[34:35]
	v_lshl_add_u64 v[34:35], v[128:129], 0, s[36:37]
	global_load_dwordx2 v[136:137], v[34:35], off offset:-64
	global_load_dwordx2 v[134:135], v[34:35], off offset:-32
	global_load_dwordx2 v[132:133], v[34:35], off
	global_load_dwordx2 v[130:131], v[34:35], off offset:32
	s_cmpk_eq_i32 s1, 0xe00
	s_waitcnt lgkmcnt(0)
	s_barrier
	s_cbranch_scc1 .LBB0_424
	s_ashr_i32 s45, s44, 31
	s_lshl_b64 s[28:29], s[44:45], 15
	v_lshl_add_u64 v[34:35], v[118:119], 0, s[28:29]
	v_lshl_add_u64 v[52:53], v[110:111], 2, v[34:35]
	v_lshl_add_u64 v[56:57], v[112:113], 2, v[34:35]
	v_lshl_add_u64 v[60:61], v[114:115], 2, v[34:35]
	global_load_dwordx4 v[52:55], v[52:53], off
	s_nop 0
	global_load_dwordx4 v[56:59], v[56:57], off
	v_lshl_add_u64 v[34:35], v[116:117], 2, v[34:35]
	global_load_dwordx4 v[60:63], v[60:61], off
	s_nop 0
	global_load_dwordx4 v[64:67], v[34:35], off

.LBB0_432:
	ds_read_b128 v[80:83], v166
	ds_read_b128 v[172:175], v166 offset:64
	ds_read_b128 v[88:91], v166 offset:4352
	ds_read_b128 v[92:95], v166 offset:8704
	ds_read_b128 v[96:99], v166 offset:13056
	s_waitcnt lgkmcnt(5)
	v_mul_f32_e32 v32, 0x3fb8aa3b, v138
	global_load_dword v138, v33, s[42:43]
	v_exp_f32_e32 v34, v32
	s_waitcnt lgkmcnt(4)
	v_mfma_f32_16x16x32_bf16 v[80:83], v[80:83], v[0:3], 0
	s_waitcnt lgkmcnt(3)
	v_mfma_f32_16x16x32_bf16 v[80:83], v[172:175], v[4:7], v[80:83]
	ds_read_b128 v[172:175], v166 offset:4416
	s_waitcnt lgkmcnt(3)
	v_mfma_f32_16x16x32_bf16 v[88:91], v[88:91], v[0:3], 0
	s_waitcnt lgkmcnt(0)
	v_mfma_f32_16x16x32_bf16 v[88:91], v[172:175], v[4:7], v[88:91]
	ds_read_b128 v[172:175], v166 offset:8768
	v_mfma_f32_16x16x32_bf16 v[92:95], v[92:95], v[0:3], 0
	s_waitcnt lgkmcnt(0)
	v_mfma_f32_16x16x32_bf16 v[92:95], v[172:175], v[4:7], v[92:95]
	ds_read_b128 v[172:175], v166 offset:13120
	v_mfma_f32_16x16x32_bf16 v[96:99], v[96:99], v[0:3], 0
	s_waitcnt lgkmcnt(0)
	v_mfma_f32_16x16x32_bf16 v[96:99], v[172:175], v[4:7], v[96:99]
	ds_read_b128 v[172:175], v166 offset:128
	s_waitcnt lgkmcnt(0)
	v_mfma_f32_16x16x32_bf16 v[80:83], v[172:175], v[8:11], v[80:83]
	ds_read_b128 v[172:175], v166 offset:4480
	s_waitcnt lgkmcnt(0)
	v_mfma_f32_16x16x32_bf16 v[88:91], v[172:175], v[8:11], v[88:91]
	ds_read_b128 v[172:175], v166 offset:8832
	s_waitcnt lgkmcnt(0)
	v_mfma_f32_16x16x32_bf16 v[172:175], v[172:175], v[8:11], v[92:95]
	s_nop 2
	ds_read_b128 v[92:95], v166 offset:13184
	s_waitcnt lgkmcnt(0)
	v_mfma_f32_16x16x32_bf16 v[176:179], v[92:95], v[8:11], v[96:99]
	ds_read_b128 v[92:95], v166 offset:192
	s_waitcnt lgkmcnt(0)
	v_mfma_f32_16x16x32_bf16 v[96:99], v[92:95], v[12:15], v[80:83]
	s_nop 2
	ds_read_b128 v[80:83], v166 offset:4544
	s_waitcnt lgkmcnt(0)
	v_mfma_f32_16x16x32_bf16 v[92:95], v[80:83], v[12:15], v[88:91]
	ds_read_b128 v[80:83], v166 offset:8896
	s_waitcnt lgkmcnt(0)
	v_mfma_f32_16x16x32_bf16 v[88:91], v[80:83], v[12:15], v[172:175]
	s_waitcnt vmcnt(4)
	s_nop 1
	v_lshlrev_b32_e32 v172, 16, v136
	v_mul_f32_e32 v32, 0xbfb8aa3b, v172
	ds_read_b128 v[80:83], v166 offset:13248
	v_exp_f32_e32 v32, v32
	v_and_b32_e32 v173, 0xffff0000, v136
	s_waitcnt lgkmcnt(0)
	v_mfma_f32_16x16x32_bf16 v[80:83], v[80:83], v[12:15], v[176:179]
	v_add_f32_e32 v32, 1.0, v32
	v_rcp_f32_e32 v174, v32
	ds_read_u16 v32, v170
	ds_read_u16 v35, v170 offset:272
	s_waitcnt lgkmcnt(1)
	v_lshlrev_b32_e32 v176, 16, v32
	v_mul_f32_e32 v32, 0xbfb8aa3b, v173
	v_exp_f32_e32 v32, v32
	s_waitcnt lgkmcnt(0)
	v_lshlrev_b32_e32 v177, 16, v35
	v_pk_fma_f32 v[84:85], v[34:35], v[96:97], v[84:85] op_sel_hi:[0,1,1]
	s_waitcnt vmcnt(0)
	v_pk_fma_f32 v[84:85], v[138:139], v[176:177], v[84:85] op_sel_hi:[0,1,1]
	v_add_f32_e32 v32, 1.0, v32
	v_rcp_f32_e32 v175, v32
	s_nop 0
	v_pk_mul_f32 v[96:97], v[174:175], v[172:173]
	s_nop 0
	v_pk_mul_f32 v[84:85], v[96:97], v[84:85]
	v_lshlrev_b32_e32 v96, 16, v137
	v_mul_f32_e32 v32, 0xbfb8aa3b, v96
	v_exp_f32_e32 v32, v32
	v_and_b32_e32 v97, 0xffff0000, v137
	v_add_f32_e32 v32, 1.0, v32
	v_rcp_f32_e32 v136, v32
	ds_read_u16 v32, v170 offset:544
	ds_read_u16 v35, v170 offset:816
	s_waitcnt lgkmcnt(1)
	v_lshlrev_b32_e32 v172, 16, v32
	v_mul_f32_e32 v32, 0xbfb8aa3b, v97
	v_exp_f32_e32 v32, v32
	s_waitcnt lgkmcnt(0)
	v_lshlrev_b32_e32 v173, 16, v35
	v_pk_fma_f32 v[86:87], v[34:35], v[98:99], v[86:87] op_sel_hi:[0,1,1]
	v_pk_fma_f32 v[86:87], v[138:139], v[172:173], v[86:87] op_sel_hi:[0,1,1]
	v_add_f32_e32 v32, 1.0, v32
	v_rcp_f32_e32 v137, v32
	s_nop 0
	v_pk_mul_f32 v[96:97], v[136:137], v[96:97]
	s_nop 0
	v_pk_mul_f32 v[86:87], v[96:97], v[86:87]
	s_and_saveexec_b64 s[28:29], s[46:47]
	s_cbranch_execz .LBB0_434
	v_cvt_pk_bf16_f32 v96, v84, v85
	v_cvt_pk_bf16_f32 v97, v86, v87
	v_lshl_add_u64 v[98:99], v[126:127], 0, s[36:37]
	global_store_dwordx2 v[98:99], v[96:97], off
.LBB0_434:
	s_or_b64 exec, exec, s[28:29]
	v_lshlrev_b32_e32 v96, 16, v134
	v_mul_f32_e32 v32, 0xbfb8aa3b, v96
	v_exp_f32_e32 v32, v32
	v_and_b32_e32 v97, 0xffff0000, v134
	v_mov_b32_e32 v35, v34
	v_mov_b32_e32 v139, v138
	v_add_f32_e32 v32, 1.0, v32
	v_rcp_f32_e32 v98, v32
	ds_read_u16 v32, v167
	ds_read_u16 v99, v170 offset:4624
	v_pk_fma_f32 v[76:77], v[34:35], v[92:93], v[76:77]
	v_pk_fma_f32 v[78:79], v[34:35], v[94:95], v[78:79]
	s_waitcnt lgkmcnt(1)
	v_lshlrev_b32_e32 v136, 16, v32
	v_mul_f32_e32 v32, 0xbfb8aa3b, v97
	v_exp_f32_e32 v32, v32
	s_waitcnt lgkmcnt(0)
	v_lshlrev_b32_e32 v137, 16, v99
	v_pk_fma_f32 v[76:77], v[138:139], v[136:137], v[76:77]
	v_add_f32_e32 v32, 1.0, v32
	v_rcp_f32_e32 v99, v32
	s_nop 0
	v_pk_mul_f32 v[92:93], v[98:99], v[96:97]
	s_nop 0
	v_pk_mul_f32 v[76:77], v[92:93], v[76:77]
	v_lshlrev_b32_e32 v92, 16, v135
	v_mul_f32_e32 v32, 0xbfb8aa3b, v92
	v_exp_f32_e32 v32, v32
	v_and_b32_e32 v93, 0xffff0000, v135
	v_add_f32_e32 v32, 1.0, v32
	v_rcp_f32_e32 v96, v32
	ds_read_u16 v32, v170 offset:4896
	ds_read_u16 v97, v170 offset:5168
	s_waitcnt lgkmcnt(1)
	v_lshlrev_b32_e32 v98, 16, v32
	v_mul_f32_e32 v32, 0xbfb8aa3b, v93
	v_exp_f32_e32 v32, v32
	s_waitcnt lgkmcnt(0)
	v_lshlrev_b32_e32 v99, 16, v97
	v_pk_fma_f32 v[78:79], v[138:139], v[98:99], v[78:79]
	v_add_f32_e32 v32, 1.0, v32
	v_rcp_f32_e32 v97, v32
	s_nop 0
	v_pk_mul_f32 v[92:93], v[96:97], v[92:93]
	s_nop 0
	v_pk_mul_f32 v[78:79], v[92:93], v[78:79]
	s_and_saveexec_b64 s[28:29], s[46:47]
	s_cbranch_execz .LBB0_436
	v_cvt_pk_bf16_f32 v92, v76, v77
	v_cvt_pk_bf16_f32 v93, v78, v79
	v_lshl_add_u64 v[94:95], v[124:125], 0, s[36:37]
	global_store_dwordx2 v[94:95], v[92:93], off
.LBB0_436:
	s_or_b64 exec, exec, s[28:29]
	v_lshlrev_b32_e32 v92, 16, v132
	v_mul_f32_e32 v32, 0xbfb8aa3b, v92
	v_exp_f32_e32 v32, v32
	v_and_b32_e32 v93, 0xffff0000, v132
	v_pk_fma_f32 v[72:73], v[34:35], v[88:89], v[72:73]
	v_pk_fma_f32 v[74:75], v[34:35], v[90:91], v[74:75]
	v_add_f32_e32 v32, 1.0, v32
	v_rcp_f32_e32 v94, v32
	ds_read_u16 v32, v168
	ds_read_u16 v95, v170 offset:8976
	s_waitcnt lgkmcnt(1)
	v_lshlrev_b32_e32 v96, 16, v32
	v_mul_f32_e32 v32, 0xbfb8aa3b, v93
	v_exp_f32_e32 v32, v32
	s_waitcnt lgkmcnt(0)
	v_lshlrev_b32_e32 v97, 16, v95
	v_pk_fma_f32 v[72:73], v[138:139], v[96:97], v[72:73]
	v_add_f32_e32 v32, 1.0, v32
	v_rcp_f32_e32 v95, v32
	s_nop 0
	v_pk_mul_f32 v[88:89], v[94:95], v[92:93]
	s_nop 0
	v_pk_mul_f32 v[72:73], v[88:89], v[72:73]
	v_lshlrev_b32_e32 v88, 16, v133
	v_mul_f32_e32 v32, 0xbfb8aa3b, v88
	v_exp_f32_e32 v32, v32
	v_and_b32_e32 v89, 0xffff0000, v133
	v_add_f32_e32 v32, 1.0, v32
	v_rcp_f32_e32 v92, v32
	ds_read_u16 v32, v170 offset:9248
	ds_read_u16 v93, v170 offset:9520
	s_waitcnt lgkmcnt(1)
	v_lshlrev_b32_e32 v94, 16, v32
	v_mul_f32_e32 v32, 0xbfb8aa3b, v89
	v_exp_f32_e32 v32, v32
	s_waitcnt lgkmcnt(0)
	v_lshlrev_b32_e32 v95, 16, v93
	v_pk_fma_f32 v[74:75], v[138:139], v[94:95], v[74:75]
	v_add_f32_e32 v32, 1.0, v32
	v_rcp_f32_e32 v93, v32
	s_nop 0
	v_pk_mul_f32 v[88:89], v[92:93], v[88:89]
	s_nop 0
	v_pk_mul_f32 v[74:75], v[88:89], v[74:75]
	s_and_saveexec_b64 s[28:29], s[46:47]
	s_cbranch_execz .LBB0_438
	v_cvt_pk_bf16_f32 v88, v72, v73
	v_cvt_pk_bf16_f32 v89, v74, v75
	v_lshl_add_u64 v[90:91], v[122:123], 0, s[36:37]
	global_store_dwordx2 v[90:91], v[88:89], off
.LBB0_438:
	s_or_b64 exec, exec, s[28:29]
	v_lshlrev_b32_e32 v88, 16, v130
	v_mul_f32_e32 v32, 0xbfb8aa3b, v88
	v_exp_f32_e32 v32, v32
	v_and_b32_e32 v89, 0xffff0000, v130
	v_pk_fma_f32 v[68:69], v[34:35], v[80:81], v[68:69]
	v_pk_fma_f32 v[34:35], v[34:35], v[82:83], v[70:71]
	v_add_f32_e32 v32, 1.0, v32
	v_rcp_f32_e32 v90, v32
	ds_read_u16 v32, v169
	ds_read_u16 v91, v170 offset:13328
	s_waitcnt lgkmcnt(1)
	v_lshlrev_b32_e32 v92, 16, v32
	v_mul_f32_e32 v32, 0xbfb8aa3b, v89
	v_exp_f32_e32 v32, v32
	s_waitcnt lgkmcnt(0)
	v_lshlrev_b32_e32 v93, 16, v91
	v_pk_fma_f32 v[68:69], v[138:139], v[92:93], v[68:69]
	v_add_f32_e32 v32, 1.0, v32
	v_rcp_f32_e32 v91, v32
	s_nop 0
	v_pk_mul_f32 v[80:81], v[90:91], v[88:89]
	s_nop 0
	v_pk_mul_f32 v[68:69], v[80:81], v[68:69]
	v_lshlrev_b32_e32 v80, 16, v131
	v_mul_f32_e32 v32, 0xbfb8aa3b, v80
	v_exp_f32_e32 v32, v32
	v_and_b32_e32 v81, 0xffff0000, v131
	v_add_f32_e32 v32, 1.0, v32
	v_rcp_f32_e32 v88, v32
	ds_read_u16 v32, v170 offset:13600
	ds_read_u16 v89, v170 offset:13872
	s_waitcnt lgkmcnt(1)
	v_lshlrev_b32_e32 v90, 16, v32
	v_mul_f32_e32 v32, 0xbfb8aa3b, v81
	v_exp_f32_e32 v32, v32
	s_waitcnt lgkmcnt(0)
	v_lshlrev_b32_e32 v91, 16, v89
	v_pk_fma_f32 v[34:35], v[138:139], v[90:91], v[34:35]
	v_add_f32_e32 v32, 1.0, v32
	v_rcp_f32_e32 v89, v32
	s_nop 0
	v_pk_mul_f32 v[70:71], v[88:89], v[80:81]
	s_nop 0
	v_pk_mul_f32 v[34:35], v[70:71], v[34:35]
	s_and_saveexec_b64 s[28:29], s[46:47]
	s_cbranch_execz .LBB0_413
	v_cvt_pk_bf16_f32 v70, v68, v69
	v_cvt_pk_bf16_f32 v71, v34, v35
	v_lshl_add_u64 v[80:81], v[120:121], 0, s[36:37]
	global_store_dwordx2 v[80:81], v[70:71], off
	s_branch .LBB0_413
